# attention: K/V LDS-DMA issue moved from step top into the PV MFMA stream (one piece per MFMA gap)
# speedup vs baseline: 1.0112x; 1.0112x over previous
.Lpv0_dma:
	ds_read_b64_tr_b16 v[180:181], v158 offset:0
	ds_read_b64_tr_b16 v[182:183], v158 offset:0x800
	ds_read_b64_tr_b16 v[184:185], v158 offset:0x1000
	ds_read_b64_tr_b16 v[186:187], v158 offset:0x1800
	ds_read_b64_tr_b16 v[188:189], v158 offset:0x2000
	ds_read_b64_tr_b16 v[190:191], v158 offset:0x2800
	ds_read_b64_tr_b16 v[192:193], v158 offset:0x3000
	ds_read_b64_tr_b16 v[194:195], v158 offset:0x3800
	s_waitcnt lgkmcnt(0)
	s_waitcnt lgkmcnt(0)
	v_cndmask_b32_e64 v173, v113, v121, s[2:3]
	v_cndmask_b32_e64 v172, v112, v120, s[2:3]
	v_cndmask_b32_e64 v177, v121, v113, s[2:3]
	v_cndmask_b32_e64 v176, v120, v112, s[2:3]
	v_max_f32_e32 v120, v166, v166
	v_max_f32_e32 v121, v164, v164
	v_max_f32_e32 v120, v121, v120
	v_cndmask_b32_e64 v171, v119, v127, s[2:3]
	v_cndmask_b32_e64 v170, v118, v126, s[2:3]
	v_cndmask_b32_e64 v169, v117, v125, s[2:3]
	v_cndmask_b32_e64 v168, v116, v124, s[2:3]
	v_cndmask_b32_e64 v175, v115, v123, s[2:3]
	v_cndmask_b32_e64 v174, v114, v122, s[2:3]
	v_cndmask_b32_e64 v127, v127, v119, s[2:3]
	v_cndmask_b32_e64 v126, v126, v118, s[2:3]
	v_cndmask_b32_e64 v125, v125, v117, s[2:3]
	v_cndmask_b32_e64 v124, v124, v116, s[2:3]
	v_cndmask_b32_e64 v179, v123, v115, s[2:3]
	v_cndmask_b32_e64 v178, v122, v114, s[2:3]
	s_nop 1
	v_mfma_f32_32x32x16_bf16 v[48:63], v[176:179], v[180:183], v[48:63]
	s_mov_b64 s[54:55], 0xe404000
	s_add_i32 m0, s96, 0x8000
	v_lshl_add_u64 v[228:229], v[134:135], 0, s[54:55]
	s_nop 0
	global_load_lds_dwordx4 v[228:229], off
	ds_read_b64_tr_b16 v[180:181], v158 offset:0x200
	ds_read_b64_tr_b16 v[182:183], v158 offset:0xa00
	v_mfma_f32_32x32x16_bf16 v[48:63], v[124:127], v[184:187], v[48:63]
	s_mov_b64 s[54:55], 0xe406000
	s_add_i32 m0, s96, 0xa000
	v_lshl_add_u64 v[228:229], v[134:135], 0, s[54:55]
	s_nop 0
	global_load_lds_dwordx4 v[228:229], off
	ds_read_b64_tr_b16 v[184:185], v158 offset:0x1200
	ds_read_b64_tr_b16 v[186:187], v158 offset:0x1a00
	v_mfma_f32_32x32x16_bf16 v[48:63], v[172:175], v[188:191], v[48:63]
	s_mov_b64 s[54:55], 0xe804000
	s_add_i32 m0, s96, 0xc000
	v_lshl_add_u64 v[228:229], v[134:135], 0, s[54:55]
	s_nop 0
	global_load_lds_dwordx4 v[228:229], off
	ds_read_b64_tr_b16 v[188:189], v158 offset:0x2200
	ds_read_b64_tr_b16 v[190:191], v158 offset:0x2a00
	v_mfma_f32_32x32x16_bf16 v[48:63], v[168:171], v[192:195], v[48:63]
	s_mov_b64 s[54:55], 0xe806000
	s_add_i32 m0, s96, 0xe000
	v_lshl_add_u64 v[228:229], v[134:135], 0, s[54:55]
	s_nop 0
	global_load_lds_dwordx4 v[228:229], off
	ds_read_b64_tr_b16 v[192:193], v158 offset:0x3200
	ds_read_b64_tr_b16 v[194:195], v158 offset:0x3a00
	s_waitcnt lgkmcnt(0)
	v_mfma_f32_32x32x16_bf16 v[32:47], v[176:179], v[180:183], v[32:47]
	s_cmp_gt_i32 s19, s18
	s_cbranch_scc1 .Lk0_skip
	v_lshl_add_u64 v[230:231], s[50:51], 0, v[130:131]
	s_mov_b64 s[54:55], 0xc408000
	s_mov_b32 m0, s97
	v_lshl_add_u64 v[228:229], v[230:231], 0, s[54:55]
	s_mov_b64 s[54:55], 0xc40a000
	global_load_lds_dwordx4 v[228:229], off
	s_mov_b32 m0, s26
	v_lshl_add_u64 v[230:231], v[230:231], 0, s[54:55]
	s_nop 0
	global_load_lds_dwordx4 v[230:231], off
.Lk0_skip:
	ds_read_b64_tr_b16 v[180:181], v158 offset:0x400
	ds_read_b64_tr_b16 v[182:183], v158 offset:0xc00
	v_mfma_f32_32x32x16_bf16 v[32:47], v[124:127], v[184:187], v[32:47]
	ds_read_b64_tr_b16 v[184:185], v158 offset:0x1400
	ds_read_b64_tr_b16 v[186:187], v158 offset:0x1c00
	v_mfma_f32_32x32x16_bf16 v[32:47], v[172:175], v[188:191], v[32:47]
	ds_read_b64_tr_b16 v[188:189], v158 offset:0x2400
	ds_read_b64_tr_b16 v[190:191], v158 offset:0x2c00
	v_mfma_f32_32x32x16_bf16 v[32:47], v[168:171], v[192:195], v[32:47]
	ds_read_b64_tr_b16 v[192:193], v158 offset:0x3400
	ds_read_b64_tr_b16 v[194:195], v158 offset:0x3c00
	s_waitcnt lgkmcnt(0)
	v_mfma_f32_32x32x16_bf16 v[16:31], v[176:179], v[180:183], v[16:31]
	ds_read_b64_tr_b16 v[180:181], v158 offset:0x600
	ds_read_b64_tr_b16 v[182:183], v158 offset:0xe00
	v_mfma_f32_32x32x16_bf16 v[16:31], v[124:127], v[184:187], v[16:31]
	ds_read_b64_tr_b16 v[184:185], v158 offset:0x1600
	ds_read_b64_tr_b16 v[186:187], v158 offset:0x1e00
	v_mfma_f32_32x32x16_bf16 v[16:31], v[172:175], v[188:191], v[16:31]
	ds_read_b64_tr_b16 v[188:189], v158 offset:0x2600
	ds_read_b64_tr_b16 v[190:191], v158 offset:0x2e00
	v_mfma_f32_32x32x16_bf16 v[16:31], v[168:171], v[192:195], v[16:31]
	ds_read_b64_tr_b16 v[192:193], v158 offset:0x3600
	ds_read_b64_tr_b16 v[194:195], v158 offset:0x3e00
	s_waitcnt lgkmcnt(0)
	v_mfma_f32_32x32x16_bf16 v[0:15], v[176:179], v[180:183], v[0:15]
	v_sub_f32_e32 v121, v120, v165
	v_mul_f32_e32 v121, 0x3db504f3, v121
	v_cmp_ge_f32_e32 vcc, s88, v121
	s_cmp_eq_u64 vcc, exec
	v_mfma_f32_32x32x16_bf16 v[0:15], v[124:127], v[184:187], v[0:15]
	v_mfma_f32_32x32x16_bf16 v[0:15], v[172:175], v[188:191], v[0:15]
	v_mfma_f32_32x32x16_bf16 v[0:15], v[168:171], v[192:195], v[0:15]
	s_cbranch_scc1 .LBB0_742
	s_branch .Lresc0

.Lresc0:
	v_max_f32_e32 v120, v120, v120
	v_max_f32_e32 v121, v165, v165
	v_max_f32_e32 v166, v121, v120
	v_sub_f32_e32 v120, v165, v166
	v_mul_f32_e32 v120, 0x3e0293ee, v120
	v_exp_f32_e32 v120, v120
	s_and_saveexec_b64 s[54:55], s[4:5]
	ds_write_b32 v159, v120
	s_or_b64 exec, exec, s[54:55]
	s_waitcnt lgkmcnt(0)
	v_mul_f32_e32 v155, v155, v120
	ds_read_b128 v[120:123], v161
	ds_read_b128 v[124:127], v161 offset:32
	ds_read_b128 v[168:171], v161 offset:64
	ds_read_b128 v[172:175], v161 offset:96
	s_waitcnt lgkmcnt(0)
	v_pk_mul_f32 v[50:51], v[50:51], v[122:123]
	v_pk_mul_f32 v[54:55], v[54:55], v[126:127]
	v_pk_mul_f32 v[58:59], v[58:59], v[170:171]
	v_pk_mul_f32 v[62:63], v[62:63], v[174:175]
	v_pk_mul_f32 v[60:61], v[60:61], v[172:173]
	v_pk_mul_f32 v[56:57], v[56:57], v[168:169]
	v_pk_mul_f32 v[52:53], v[52:53], v[124:125]
	v_pk_mul_f32 v[48:49], v[48:49], v[120:121]
	v_pk_mul_f32 v[46:47], v[46:47], v[174:175]
	v_pk_mul_f32 v[42:43], v[42:43], v[170:171]
	v_pk_mul_f32 v[38:39], v[38:39], v[126:127]
	v_pk_mul_f32 v[34:35], v[34:35], v[122:123]
	v_pk_mul_f32 v[44:45], v[44:45], v[172:173]
	v_pk_mul_f32 v[40:41], v[40:41], v[168:169]
	v_pk_mul_f32 v[36:37], v[36:37], v[124:125]
	v_pk_mul_f32 v[32:33], v[32:33], v[120:121]
	v_pk_mul_f32 v[30:31], v[30:31], v[174:175]
	v_pk_mul_f32 v[26:27], v[26:27], v[170:171]
	v_pk_mul_f32 v[22:23], v[22:23], v[126:127]
	v_pk_mul_f32 v[18:19], v[18:19], v[122:123]
	v_pk_mul_f32 v[28:29], v[28:29], v[172:173]
	v_pk_mul_f32 v[24:25], v[24:25], v[168:169]
	v_pk_mul_f32 v[20:21], v[20:21], v[124:125]
	v_pk_mul_f32 v[16:17], v[16:17], v[120:121]
	v_pk_mul_f32 v[14:15], v[14:15], v[174:175]
	v_pk_mul_f32 v[10:11], v[10:11], v[170:171]
	v_pk_mul_f32 v[6:7], v[6:7], v[126:127]
	v_pk_mul_f32 v[2:3], v[2:3], v[122:123]
	v_pk_mul_f32 v[12:13], v[12:13], v[172:173]
	v_pk_mul_f32 v[8:9], v[8:9], v[168:169]
	v_pk_mul_f32 v[4:5], v[4:5], v[124:125]
	v_pk_mul_f32 v[0:1], v[0:1], v[120:121]
	s_andn2_b64 vcc, exec, s[52:53]
	s_cbranch_vccz .LBB0_743
	s_branch .LBB0_748

.Lpv1_dma:
	ds_read_b64_tr_b16 v[180:181], v158 offset:0x8000
	ds_read_b64_tr_b16 v[182:183], v158 offset:0x8800
	ds_read_b64_tr_b16 v[184:185], v158 offset:0x9000
	ds_read_b64_tr_b16 v[186:187], v158 offset:0x9800
	ds_read_b64_tr_b16 v[188:189], v158 offset:0xa000
	ds_read_b64_tr_b16 v[190:191], v158 offset:0xa800
	ds_read_b64_tr_b16 v[192:193], v158 offset:0xb000
	ds_read_b64_tr_b16 v[194:195], v158 offset:0xb800
	s_waitcnt lgkmcnt(0)
	s_waitcnt lgkmcnt(0)
	v_cndmask_b32_e64 v173, v113, v121, s[2:3]
	v_cndmask_b32_e64 v172, v112, v120, s[2:3]
	v_cndmask_b32_e64 v177, v121, v113, s[2:3]
	v_cndmask_b32_e64 v176, v120, v112, s[2:3]
	v_max_f32_e32 v120, v128, v128
	v_max_f32_e32 v121, v164, v164
	v_max_f32_e32 v120, v121, v120
	v_cndmask_b32_e64 v171, v127, v119, s[2:3]
	v_cndmask_b32_e64 v170, v126, v118, s[2:3]
	v_cndmask_b32_e64 v169, v125, v117, s[2:3]
	v_cndmask_b32_e64 v168, v124, v116, s[2:3]
	v_cndmask_b32_e64 v175, v115, v123, s[2:3]
	v_cndmask_b32_e64 v174, v114, v122, s[2:3]
	v_cndmask_b32_e64 v127, v119, v127, s[2:3]
	v_cndmask_b32_e64 v126, v118, v126, s[2:3]
	v_cndmask_b32_e64 v125, v117, v125, s[2:3]
	v_cndmask_b32_e64 v124, v116, v124, s[2:3]
	v_cndmask_b32_e64 v179, v123, v115, s[2:3]
	v_cndmask_b32_e64 v178, v122, v114, s[2:3]
	s_nop 1
	v_mfma_f32_32x32x16_bf16 v[48:63], v[176:179], v[180:183], v[48:63]
	s_mov_b64 s[56:57], 0xe408000
	s_mov_b32 m0, s96
	v_lshl_add_u64 v[228:229], v[134:135], 0, s[56:57]
	s_nop 0
	global_load_lds_dwordx4 v[228:229], off
	ds_read_b64_tr_b16 v[180:181], v158 offset:0x8200
	ds_read_b64_tr_b16 v[182:183], v158 offset:0x8a00
	v_mfma_f32_32x32x16_bf16 v[48:63], v[168:171], v[184:187], v[48:63]
	s_mov_b64 s[56:57], 0xe40a000
	s_mov_b32 m0, s6
	v_lshl_add_u64 v[228:229], v[134:135], 0, s[56:57]
	s_nop 0
	global_load_lds_dwordx4 v[228:229], off
	ds_read_b64_tr_b16 v[184:185], v158 offset:0x9200
	ds_read_b64_tr_b16 v[186:187], v158 offset:0x9a00
	v_mfma_f32_32x32x16_bf16 v[48:63], v[172:175], v[188:191], v[48:63]
	s_mov_b64 s[56:57], 0xe808000
	s_mov_b32 m0, s7
	v_lshl_add_u64 v[228:229], v[134:135], 0, s[56:57]
	s_nop 0
	global_load_lds_dwordx4 v[228:229], off
	ds_read_b64_tr_b16 v[188:189], v158 offset:0xa200
	ds_read_b64_tr_b16 v[190:191], v158 offset:0xaa00
	v_mfma_f32_32x32x16_bf16 v[48:63], v[124:127], v[192:195], v[48:63]
	s_mov_b64 s[56:57], 0xe80a000
	s_mov_b32 m0, s24
	v_lshl_add_u64 v[228:229], v[134:135], 0, s[56:57]
	s_nop 0
	global_load_lds_dwordx4 v[228:229], off
	ds_read_b64_tr_b16 v[192:193], v158 offset:0xb200
	ds_read_b64_tr_b16 v[194:195], v158 offset:0xba00
	s_waitcnt lgkmcnt(0)
	v_mfma_f32_32x32x16_bf16 v[32:47], v[176:179], v[180:183], v[32:47]
	s_add_i32 s56, s19, 1
	s_cmp_gt_i32 s56, s18
	s_cbranch_scc1 .Lk1_skip
	v_lshl_add_u64 v[230:231], s[50:51], 0, v[130:131]
	s_mov_b64 s[56:57], 0xc40c000
	s_mov_b32 m0, s27
	v_lshl_add_u64 v[228:229], v[230:231], 0, s[56:57]
	s_mov_b64 s[56:57], 0xc40e000
	global_load_lds_dwordx4 v[228:229], off
	s_mov_b32 m0, s62
	v_lshl_add_u64 v[230:231], v[230:231], 0, s[56:57]
	s_nop 0
	global_load_lds_dwordx4 v[230:231], off
.Lk1_skip:
	ds_read_b64_tr_b16 v[180:181], v158 offset:0x8400
	ds_read_b64_tr_b16 v[182:183], v158 offset:0x8c00
	v_mfma_f32_32x32x16_bf16 v[32:47], v[168:171], v[184:187], v[32:47]
	ds_read_b64_tr_b16 v[184:185], v158 offset:0x9400
	ds_read_b64_tr_b16 v[186:187], v158 offset:0x9c00
	v_mfma_f32_32x32x16_bf16 v[32:47], v[172:175], v[188:191], v[32:47]
	ds_read_b64_tr_b16 v[188:189], v158 offset:0xa400
	ds_read_b64_tr_b16 v[190:191], v158 offset:0xac00
	v_mfma_f32_32x32x16_bf16 v[32:47], v[124:127], v[192:195], v[32:47]
	ds_read_b64_tr_b16 v[192:193], v158 offset:0xb400
	ds_read_b64_tr_b16 v[194:195], v158 offset:0xbc00
	s_waitcnt lgkmcnt(0)
	v_mfma_f32_32x32x16_bf16 v[16:31], v[176:179], v[180:183], v[16:31]
	ds_read_b64_tr_b16 v[180:181], v158 offset:0x8600
	ds_read_b64_tr_b16 v[182:183], v158 offset:0x8e00
	v_mfma_f32_32x32x16_bf16 v[16:31], v[168:171], v[184:187], v[16:31]
	ds_read_b64_tr_b16 v[184:185], v158 offset:0x9600
	ds_read_b64_tr_b16 v[186:187], v158 offset:0x9e00
	v_mfma_f32_32x32x16_bf16 v[16:31], v[172:175], v[188:191], v[16:31]
	ds_read_b64_tr_b16 v[188:189], v158 offset:0xa600
	ds_read_b64_tr_b16 v[190:191], v158 offset:0xae00
	v_mfma_f32_32x32x16_bf16 v[16:31], v[124:127], v[192:195], v[16:31]
	ds_read_b64_tr_b16 v[192:193], v158 offset:0xb600
	ds_read_b64_tr_b16 v[194:195], v158 offset:0xbe00
	s_waitcnt lgkmcnt(0)
	v_mfma_f32_32x32x16_bf16 v[0:15], v[176:179], v[180:183], v[0:15]
	v_sub_f32_e32 v121, v120, v166
	v_mul_f32_e32 v121, 0x3db504f3, v121
	v_cmp_ge_f32_e32 vcc, s88, v121
	s_cmp_eq_u64 vcc, exec
	v_mfma_f32_32x32x16_bf16 v[0:15], v[168:171], v[184:187], v[0:15]
	v_mfma_f32_32x32x16_bf16 v[0:15], v[172:175], v[188:191], v[0:15]
	v_mfma_f32_32x32x16_bf16 v[0:15], v[124:127], v[192:195], v[0:15]
	s_cbranch_scc1 .LBB0_756
	s_branch .Lresc1

.Lresc1:
	v_max_f32_e32 v120, v120, v120
	v_max_f32_e32 v121, v166, v166
	v_max_f32_e32 v165, v121, v120
	v_sub_f32_e32 v120, v166, v165
	v_mul_f32_e32 v120, 0x3e0293ee, v120
	v_exp_f32_e32 v120, v120
	s_and_saveexec_b64 s[56:57], s[4:5]
	ds_write_b32 v159, v120
	s_or_b64 exec, exec, s[56:57]
	s_waitcnt lgkmcnt(0)
	v_mul_f32_e32 v155, v155, v120
	ds_read_b128 v[120:123], v161
	ds_read_b128 v[124:127], v161 offset:32
	ds_read_b128 v[166:169], v161 offset:64
	ds_read_b128 v[170:173], v161 offset:96
	s_waitcnt lgkmcnt(0)
	v_pk_mul_f32 v[50:51], v[50:51], v[122:123]
	v_pk_mul_f32 v[54:55], v[54:55], v[126:127]
	v_pk_mul_f32 v[58:59], v[58:59], v[168:169]
	v_pk_mul_f32 v[62:63], v[62:63], v[172:173]
	v_pk_mul_f32 v[60:61], v[60:61], v[170:171]
	v_pk_mul_f32 v[56:57], v[56:57], v[166:167]
	v_pk_mul_f32 v[52:53], v[52:53], v[124:125]
	v_pk_mul_f32 v[48:49], v[48:49], v[120:121]
	v_pk_mul_f32 v[46:47], v[46:47], v[172:173]
	v_pk_mul_f32 v[42:43], v[42:43], v[168:169]
	v_pk_mul_f32 v[38:39], v[38:39], v[126:127]
	v_pk_mul_f32 v[34:35], v[34:35], v[122:123]
	v_pk_mul_f32 v[44:45], v[44:45], v[170:171]
	v_pk_mul_f32 v[40:41], v[40:41], v[166:167]
	v_pk_mul_f32 v[36:37], v[36:37], v[124:125]
	v_pk_mul_f32 v[32:33], v[32:33], v[120:121]
	v_pk_mul_f32 v[30:31], v[30:31], v[172:173]
	v_pk_mul_f32 v[26:27], v[26:27], v[168:169]
	v_pk_mul_f32 v[22:23], v[22:23], v[126:127]
	v_pk_mul_f32 v[18:19], v[18:19], v[122:123]
	v_pk_mul_f32 v[28:29], v[28:29], v[170:171]
	v_pk_mul_f32 v[24:25], v[24:25], v[166:167]
	v_pk_mul_f32 v[20:21], v[20:21], v[124:125]
	v_pk_mul_f32 v[16:17], v[16:17], v[120:121]
	v_pk_mul_f32 v[14:15], v[14:15], v[172:173]
	v_pk_mul_f32 v[10:11], v[10:11], v[168:169]
	v_pk_mul_f32 v[6:7], v[6:7], v[126:127]
	v_pk_mul_f32 v[2:3], v[2:3], v[122:123]
	v_pk_mul_f32 v[12:13], v[12:13], v[170:171]
	v_pk_mul_f32 v[8:9], v[8:9], v[166:167]
	v_pk_mul_f32 v[4:5], v[4:5], v[124:125]
	v_pk_mul_f32 v[0:1], v[0:1], v[120:121]
	s_andn2_b64 vcc, exec, s[54:55]
	s_cbranch_vccnz .LBB0_733
	s_branch .LBB0_757

	.amdhsa_kernel _Z8mega_fwd4Args
		.amdhsa_group_segment_fixed_size 0
		.amdhsa_private_segment_fixed_size 0
		.amdhsa_kernarg_size 464
		.amdhsa_user_sgpr_count 2
		.amdhsa_user_sgpr_dispatch_ptr 0
		.amdhsa_user_sgpr_queue_ptr 0
		.amdhsa_user_sgpr_kernarg_segment_ptr 1
		.amdhsa_user_sgpr_dispatch_id 0
		.amdhsa_user_sgpr_kernarg_preload_length 0
		.amdhsa_user_sgpr_kernarg_preload_offset 0
		.amdhsa_user_sgpr_private_segment_size 0
		.amdhsa_uses_dynamic_stack 0
		.amdhsa_enable_private_segment 0
		.amdhsa_system_sgpr_workgroup_id_x 1
		.amdhsa_system_sgpr_workgroup_id_y 0
		.amdhsa_system_sgpr_workgroup_id_z 0
		.amdhsa_system_sgpr_workgroup_info 0
		.amdhsa_system_vgpr_workitem_id 2
		.amdhsa_next_free_vgpr 232
		.amdhsa_next_free_sgpr 98
		.amdhsa_accum_offset 232
		.amdhsa_reserve_vcc 1
		.amdhsa_float_round_mode_32 0
		.amdhsa_float_round_mode_16_64 0
		.amdhsa_float_denorm_mode_32 3
		.amdhsa_float_denorm_mode_16_64 3
		.amdhsa_dx10_clamp 1
		.amdhsa_ieee_mode 1
		.amdhsa_fp16_overflow 0
		.amdhsa_tg_split 0
		.amdhsa_exception_fp_ieee_invalid_op 0
		.amdhsa_exception_fp_denorm_src 0
		.amdhsa_exception_fp_ieee_div_zero 0
		.amdhsa_exception_fp_ieee_overflow 0
		.amdhsa_exception_fp_ieee_underflow 0
		.amdhsa_exception_fp_ieee_inexact 0
		.amdhsa_exception_int_div_zero 0
	.end_amdhsa_kernel

amdhsa.kernels:
  - .agpr_count:     0
    .args:
      - .offset:         0
        .size:           208
        .value_kind:     by_value
      - .offset:         208
        .size:           4
        .value_kind:     hidden_block_count_x
      - .offset:         212
        .size:           4
        .value_kind:     hidden_block_count_y
      - .offset:         216
        .size:           4
        .value_kind:     hidden_block_count_z
      - .offset:         220
        .size:           2
        .value_kind:     hidden_group_size_x
      - .offset:         222
        .size:           2
        .value_kind:     hidden_group_size_y
      - .offset:         224
        .size:           2
        .value_kind:     hidden_group_size_z
      - .offset:         226
        .size:           2
        .value_kind:     hidden_remainder_x
      - .offset:         228
        .size:           2
        .value_kind:     hidden_remainder_y
      - .offset:         230
        .size:           2
        .value_kind:     hidden_remainder_z
      - .offset:         248
        .size:           8
        .value_kind:     hidden_global_offset_x
      - .offset:         256
        .size:           8
        .value_kind:     hidden_global_offset_y
      - .offset:         264
        .size:           8
        .value_kind:     hidden_global_offset_z
      - .offset:         272
        .size:           2
        .value_kind:     hidden_grid_dims
      - .offset:         296
        .size:           8
        .value_kind:     hidden_multigrid_sync_arg
      - .offset:         328
        .size:           4
        .value_kind:     hidden_dynamic_lds_size
    .group_segment_fixed_size: 0
    .kernarg_segment_align: 8
    .kernarg_segment_size: 464
    .language:       OpenCL C
    .language_version:
      - 2
      - 0
    .max_flat_workgroup_size: 512
    .name:           _Z8mega_fwd4Args
    .private_segment_fixed_size: 0
    .sgpr_count:     104
    .sgpr_spill_count: 8
    .symbol:         _Z8mega_fwd4Args.kd
    .uniform_work_group_size: 1
    .uses_dynamic_stack: false
    .vgpr_count:     232
    .vgpr_spill_count: 0
    .wavefront_size: 64
